# v053 + first K iteration of every tile peeled with C=0 MFMAs so the 128-register accumulator zeroing per tile goes
# baseline (speedup 1.0000x reference)
.Lkexit_311:
	v_lshl_add_u32 v140, s2, 8, v142
	v_ashrrev_i32_e32 v141, 31, v140
	v_lshl_add_u64 v[156:157], v[140:141], 4, s[48:49]
	global_load_dwordx4 v[208:211], v[156:157], off
	global_load_dwordx4 v[212:215], v[156:157], off offset:256
	global_load_dwordx4 v[216:219], v[156:157], off offset:512
	global_load_dwordx4 v[220:223], v[156:157], off offset:768
	global_load_dwordx4 v[224:227], v[156:157], off offset:2048
	global_load_dwordx4 v[228:231], v[156:157], off offset:2304
	global_load_dwordx4 v[232:235], v[156:157], off offset:2560
	global_load_dwordx4 v[236:239], v[156:157], off offset:2816
	s_and_b64 vcc, exec, s[50:51]
	s_cbranch_vccz .LBB0_314
	s_barrier

.Lkexit_1305:
	v_lshl_add_u32 v140, s58, 8, v142
	v_ashrrev_i32_e32 v141, 31, v140
	v_lshl_add_u64 v[156:157], v[140:141], 4, s[44:45]
	global_load_dwordx4 v[208:211], v[156:157], off
	global_load_dwordx4 v[212:215], v[156:157], off offset:256
	global_load_dwordx4 v[216:219], v[156:157], off offset:512
	global_load_dwordx4 v[220:223], v[156:157], off offset:768
	global_load_dwordx4 v[224:227], v[156:157], off offset:2048
	global_load_dwordx4 v[228:231], v[156:157], off offset:2304
	global_load_dwordx4 v[232:235], v[156:157], off offset:2560
	global_load_dwordx4 v[236:239], v[156:157], off offset:2816
	s_and_b64 vcc, exec, s[46:47]
	s_cbranch_vccz .LBB0_1308
	s_barrier
